# P0 rows loop: x row loads use nt (streaming) policy; row-0 loads drained before row-1 loads
# speedup vs baseline: 1.0336x; 1.0166x over previous
.LBB0_38:
	s_add_i32 s28, s56, s58
	s_cmpk_lt_i32 s28, 0x4000
	s_cselect_b32 s16, s28, s56
	s_ashr_i32 s57, s56, 31
	s_lshl_b64 s[46:47], s[56:57], 12
	v_lshl_add_u64 v[34:35], v[2:3], 0, s[46:47]
	global_load_dwordx4 v[18:21], v[4:5], off
	s_ashr_i32 s17, s16, 31
	global_load_dwordx4 v[22:25], v[34:35], off nt
	global_load_dwordx4 v[26:29], v[34:35], off offset:1024 nt
	global_load_dwordx4 v[30:33], v[34:35], off offset:3072 nt
	s_nop 0
	global_load_dwordx4 v[34:37], v[34:35], off offset:2048 nt
	s_lshl_b64 s[0:1], s[56:57], 10
	s_lshl_b64 s[50:51], s[16:17], 12
	s_lshl_b64 s[46:47], s[16:17], 10
	v_lshl_add_u64 v[38:39], v[6:7], 0, s[0:1]
	v_lshl_add_u64 v[64:65], v[2:3], 0, s[50:51]
	global_load_dwordx4 v[38:41], v[38:39], off nt
	s_waitcnt vmcnt(0)
	v_lshl_add_u64 v[66:67], v[6:7], 0, s[46:47]
	global_load_dwordx4 v[42:45], v[64:65], off nt
	global_load_dwordx4 v[46:49], v[64:65], off offset:1024 nt
	global_load_dwordx4 v[50:53], v[64:65], off offset:3072 nt
	global_load_dwordx4 v[54:57], v[64:65], off offset:2048 nt
	global_load_dwordx4 v[58:61], v[66:67], off nt
	s_lshl_b64 s[0:1], s[16:17], 11
	v_lshl_add_u64 v[68:69], v[8:9], 0, s[0:1]
	s_lshl_b64 s[48:49], s[56:57], 11
	v_lshl_add_u64 v[62:63], v[8:9], 0, s[48:49]
	s_waitcnt vmcnt(9)
	v_pk_mul_f32 v[64:65], v[24:25], v[24:25]
	v_pk_mul_f32 v[66:67], v[22:23], v[22:23]
	s_waitcnt vmcnt(8)
	v_pk_mul_f32 v[70:71], v[28:29], v[28:29]
	v_pk_mul_f32 v[72:73], v[26:27], v[26:27]
	s_waitcnt vmcnt(6)
	v_mul_f32_e32 v74, v35, v35
	v_mul_f32_e32 v76, v37, v37
	v_pk_mov_b32 v[78:79], v[66:67], v[64:65] op_sel:[1,0]
	v_mov_b32_e32 v67, v65
	s_waitcnt vmcnt(4)
	v_pk_mul_f32 v[64:65], v[44:45], v[44:45]
	v_pk_mul_f32 v[80:81], v[42:43], v[42:43]
	v_pk_mov_b32 v[82:83], v[72:73], v[70:71] op_sel:[1,0]
	v_mov_b32_e32 v73, v71
	s_waitcnt vmcnt(3)
	v_pk_mul_f32 v[70:71], v[48:49], v[48:49]
	v_pk_mul_f32 v[84:85], v[46:47], v[46:47]
	v_mul_f32_e32 v89, v32, v32
	v_mul_f32_e32 v90, v33, v33
	v_pk_fma_f32 v[74:75], v[34:35], v[34:35], v[74:75] op_sel_hi:[1,1,0]
	v_pk_fma_f32 v[76:77], v[36:37], v[36:37], v[76:77] op_sel_hi:[1,1,0]
	v_pk_add_f32 v[66:67], v[78:79], v[66:67]
	v_pk_mov_b32 v[78:79], v[80:81], v[64:65] op_sel:[1,0]
	v_mov_b32_e32 v81, v65
	v_pk_add_f32 v[64:65], v[82:83], v[72:73]
	v_pk_mov_b32 v[72:73], v[84:85], v[70:71] op_sel:[1,0]
	v_mov_b32_e32 v85, v71
	v_mul_f32_e32 v87, v31, v31
	s_waitcnt vmcnt(1)
	v_mul_f32_e32 v86, v55, v55
	v_mul_f32_e32 v88, v57, v57
	v_mov_b32_e32 v75, v89
	v_mov_b32_e32 v77, v90
	v_pk_add_f32 v[78:79], v[78:79], v[80:81]
	v_pk_add_f32 v[72:73], v[72:73], v[84:85]
	v_mul_f32_e32 v17, v30, v30
	v_mul_f32_e32 v91, v50, v50
	v_mul_f32_e32 v92, v51, v51
	v_mul_f32_e32 v93, v52, v52
	v_mul_f32_e32 v94, v53, v53
	v_pk_fma_f32 v[70:71], v[54:55], v[54:55], v[86:87] op_sel_hi:[1,1,0]
	v_pk_fma_f32 v[82:83], v[56:57], v[56:57], v[88:89] op_sel_hi:[1,1,0]
	v_pk_add_f32 v[66:67], v[66:67], v[66:67] op_sel:[0,1] op_sel_hi:[1,0]
	v_pk_add_f32 v[64:65], v[64:65], v[64:65] op_sel:[0,1] op_sel_hi:[1,0]
	v_pk_add_f32 v[74:75], v[74:75], v[76:77]
	v_pk_add_f32 v[76:77], v[78:79], v[78:79] op_sel:[0,1] op_sel_hi:[1,0]
	v_pk_add_f32 v[72:73], v[72:73], v[72:73] op_sel:[0,1] op_sel_hi:[1,0]
	v_mov_b32_e32 v71, v93
	v_mov_b32_e32 v83, v94
	v_mov_b32_e32 v67, v17
	v_mov_b32_e32 v65, v87
	v_mov_b32_e32 v77, v91
	v_mov_b32_e32 v73, v92
	v_pk_add_f32 v[70:71], v[70:71], v[82:83]
	v_pk_add_f32 v[64:65], v[66:67], v[64:65]
	v_pk_add_f32 v[66:67], v[76:77], v[72:73]
	v_pk_add_f32 v[64:65], v[64:65], v[74:75]
	v_pk_add_f32 v[66:67], v[66:67], v[70:71]
	v_mov_b32_e32 v71, v64
	v_mov_b32_e32 v70, v66
	v_mov_b32_e32 v64, v67
	v_pk_add_f32 v[64:65], v[70:71], v[64:65]
	ds_bpermute_b32 v67, v11, v65
	ds_bpermute_b32 v66, v11, v64
	s_waitcnt lgkmcnt(0)
	v_pk_add_f32 v[64:65], v[64:65], v[66:67]
	ds_bpermute_b32 v67, v12, v65
	ds_bpermute_b32 v66, v12, v64
	s_waitcnt lgkmcnt(0)
	v_pk_add_f32 v[64:65], v[64:65], v[66:67]
	ds_bpermute_b32 v67, v13, v65
	ds_bpermute_b32 v66, v13, v64
	s_waitcnt lgkmcnt(0)
	v_pk_add_f32 v[64:65], v[64:65], v[66:67]
	ds_bpermute_b32 v67, v14, v65
	ds_bpermute_b32 v66, v14, v64
	s_waitcnt lgkmcnt(0)
	v_pk_add_f32 v[64:65], v[64:65], v[66:67]
	ds_bpermute_b32 v67, v15, v65
	ds_bpermute_b32 v66, v15, v64
	s_waitcnt lgkmcnt(0)
	v_pk_add_f32 v[64:65], v[64:65], v[66:67]
	ds_bpermute_b32 v67, v16, v65
	ds_bpermute_b32 v66, v16, v64
	s_waitcnt lgkmcnt(0)
	v_pk_add_f32 v[64:65], v[64:65], v[66:67]
	s_nop 0
	v_pk_fma_f32 v[64:65], v[64:65], s[14:15], v[10:11] op_sel_hi:[1,0,0]
	s_nop 0
	v_mul_f32_e32 v17, 0x4b800000, v65
	v_cmp_gt_f32_e64 s[0:1], s15, v65
	v_mul_f32_e32 v66, 0x4b800000, v64
	v_cmp_gt_f32_e32 vcc, s15, v64
	v_cndmask_b32_e64 v17, v65, v17, s[0:1]
	v_rsq_f32_e32 v17, v17
	v_cndmask_b32_e32 v64, v64, v66, vcc
	v_rsq_f32_e32 v65, v64
	v_mul_f32_e32 v64, 0x45800000, v17
	v_cndmask_b32_e64 v64, v17, v64, s[0:1]
	v_mul_f32_e32 v66, 0x45800000, v65
	v_cndmask_b32_e32 v66, v65, v66, vcc
	v_pk_mul_f32 v[22:23], v[64:65], v[22:23] op_sel_hi:[0,1]
	v_pk_mul_f32 v[24:25], v[64:65], v[24:25] op_sel_hi:[0,1]
	v_pk_mul_f32 v[42:43], v[66:67], v[42:43] op_sel_hi:[0,1]
	v_pk_mul_f32 v[44:45], v[66:67], v[44:45] op_sel_hi:[0,1]
	v_pk_mul_f32 v[24:25], v[24:25], v[20:21]
	v_pk_mul_f32 v[22:23], v[22:23], v[18:19]
	v_pk_mul_f32 v[20:21], v[44:45], v[20:21]
	v_pk_mul_f32 v[18:19], v[42:43], v[18:19]
	v_cvt_pk_bf16_f32 v22, v22, v23
	v_cvt_pk_bf16_f32 v23, v24, v25
	v_cvt_pk_bf16_f32 v18, v18, v19
	v_cvt_pk_bf16_f32 v19, v20, v21
	global_store_dwordx2 v[62:63], v[22:23], off
	global_store_dwordx2 v[68:69], v[18:19], off
	global_load_dwordx4 v[18:21], v[4:5], off offset:1024
	v_pk_mul_f32 v[22:23], v[64:65], v[26:27] op_sel_hi:[0,1]
	v_pk_mul_f32 v[24:25], v[64:65], v[28:29] op_sel_hi:[0,1]
	v_pk_mul_f32 v[26:27], v[66:67], v[46:47] op_sel_hi:[0,1]
	v_pk_mul_f32 v[28:29], v[66:67], v[48:49] op_sel_hi:[0,1]
	s_lshl_b64 s[0:1], s[56:57], 9
	v_pk_mul_f32 v[30:31], v[64:65], v[30:31] op_sel_hi:[0,1]
	v_pk_mul_f32 v[32:33], v[64:65], v[32:33] op_sel_hi:[0,1]
	s_add_i32 s56, s28, s58
	s_waitcnt vmcnt(0)
	v_pk_mul_f32 v[24:25], v[24:25], v[20:21]
	v_pk_mul_f32 v[22:23], v[22:23], v[18:19]
	v_pk_mul_f32 v[20:21], v[28:29], v[20:21]
	v_pk_mul_f32 v[18:19], v[26:27], v[18:19]
	v_cvt_pk_bf16_f32 v22, v22, v23
	v_cvt_pk_bf16_f32 v23, v24, v25
	v_cvt_pk_bf16_f32 v18, v18, v19
	v_cvt_pk_bf16_f32 v19, v20, v21
	global_store_dwordx2 v[62:63], v[22:23], off offset:512
	global_store_dwordx2 v[68:69], v[18:19], off offset:512
	global_load_dwordx4 v[18:21], v[4:5], off offset:2048
	v_pk_mul_f32 v[22:23], v[64:65], v[34:35] op_sel_hi:[0,1]
	v_pk_mul_f32 v[24:25], v[64:65], v[36:37] op_sel_hi:[0,1]
	v_pk_mul_f32 v[26:27], v[66:67], v[54:55] op_sel_hi:[0,1]
	v_pk_mul_f32 v[28:29], v[66:67], v[56:57] op_sel_hi:[0,1]
	v_pk_mul_f32 v[34:35], v[66:67], v[50:51] op_sel_hi:[0,1]
	v_pk_mul_f32 v[36:37], v[66:67], v[52:53] op_sel_hi:[0,1]
	s_waitcnt vmcnt(0)
	v_pk_mul_f32 v[24:25], v[24:25], v[20:21]
	v_pk_mul_f32 v[22:23], v[22:23], v[18:19]
	v_pk_mul_f32 v[20:21], v[28:29], v[20:21]
	v_pk_mul_f32 v[18:19], v[26:27], v[18:19]
	v_cvt_pk_bf16_f32 v22, v22, v23
	v_cvt_pk_bf16_f32 v23, v24, v25
	v_cvt_pk_bf16_f32 v18, v18, v19
	v_cvt_pk_bf16_f32 v19, v20, v21
	global_store_dwordx2 v[62:63], v[22:23], off offset:1024
	global_store_dwordx2 v[68:69], v[18:19], off offset:1024
	global_load_dwordx4 v[18:21], v[4:5], off offset:3072
	v_lshl_add_u64 v[22:23], v[0:1], 0, s[0:1]
	s_lshl_b64 s[0:1], s[16:17], 9
	s_cmpk_gt_i32 s56, 0x3fff
	v_lshl_add_u64 v[24:25], v[0:1], 0, s[0:1]
	v_cvt_pk_bf16_f32 v26, v38, v39
	v_cvt_pk_bf16_f32 v27, v40, v41
	v_cvt_pk_bf16_f32 v28, v58, v59
	v_cvt_pk_bf16_f32 v29, v60, v61
	s_waitcnt vmcnt(0)
	v_pk_mul_f32 v[32:33], v[32:33], v[20:21]
	v_pk_mul_f32 v[30:31], v[30:31], v[18:19]
	v_pk_mul_f32 v[20:21], v[36:37], v[20:21]
	v_pk_mul_f32 v[18:19], v[34:35], v[18:19]
	v_cvt_pk_bf16_f32 v30, v30, v31
	v_cvt_pk_bf16_f32 v31, v32, v33
	v_cvt_pk_bf16_f32 v18, v18, v19
	v_cvt_pk_bf16_f32 v19, v20, v21
	global_store_dwordx2 v[62:63], v[30:31], off offset:1536
	global_store_dwordx2 v[68:69], v[18:19], off offset:1536
	global_store_dwordx2 v[22:23], v[26:27], off
	global_store_dwordx2 v[24:25], v[28:29], off
	s_cbranch_scc0 .LBB0_38
